# GEMM unit heads: generic float-reciprocal division by the row-group size (always 8 for M=16384) replaced by shift and mask (29 instructions per unit)
# speedup vs baseline: 1.0062x; 1.0006x over previous
.LBB0_325:
	s_add_i32 s44, s44, 1
	s_mul_i32 s6, s44, s15
	s_mul_hi_u32 s7, s44, s3
	s_add_i32 s7, s7, s6
	s_mul_i32 s6, s44, s3
	s_add_u32 s24, s6, s94
	s_addc_u32 s25, s7, s13
	v_cmp_gt_i64_e32 vcc, s[24:25], v[212:213]
	v_cmp_lt_i64_e64 s[6:7], s[24:25], v[210:211]
	s_cbranch_vccnz .LBB0_327
	s_ashr_i32 s20, s24, 31
	s_lshr_b32 s20, s20, 29
	s_add_i32 s20, s24, s20
	s_ashr_i32 s21, s20, 3
	s_and_b32 s20, s20, -8
	s_sub_i32 s20, s24, s20
	s_cmp_lt_i32 s20, 0
	s_cselect_b32 s22, s33, 0xb0
	s_mul_i32 s20, s20, s22
	s_add_i32 s20, s20, s21
	s_mul_hi_i32 s21, s20, 0x2e8ba2e9
	s_lshr_b32 s22, s21, 31
	s_ashr_i32 s21, s21, 5
	s_add_i32 s21, s21, s22
	s_lshl_b32 s22, s21, 3
	s_sub_i32 s23, 64, s22
	s_min_i32 s23, s23, 8
	s_mulk_i32 s21, 0xb0
	s_sub_i32 s21, s20, s21
	s_lshr_b32 s20, s21, 3
	s_and_b32 s21, s21, 7
	s_add_i32 s22, s22, s21

.LBB0_363:
	s_ashr_i32 s2, s2, 3
	s_add_i32 s2, s47, s2
	s_ashr_i32 s4, s2, 31
	s_lshr_b32 s4, s4, 27
	s_add_i32 s4, s2, s4
	s_ashr_i32 s5, s4, 5
	s_lshl_b32 s5, s5, 3
	s_sub_i32 s46, 64, s5
	s_min_i32 s47, s46, 8
	s_andn2_b32 s4, s4, 31
	s_sub_i32 s2, s2, s4
	s_lshr_b32 s46, s2, 3
	s_and_b32 s2, s2, 7
	s_add_i32 s48, s5, s2

.LBB0_613:
	s_ashr_i32 s6, s22, 3
	s_add_i32 s6, s26, s6
	s_ashr_i32 s7, s6, 31
	s_lshr_b32 s7, s7, 27
	s_add_i32 s7, s6, s7
	s_ashr_i32 s22, s7, 5
	s_lshl_b32 s22, s22, 3
	s_sub_i32 s23, 64, s22
	s_min_i32 s23, s23, 8
	s_andn2_b32 s7, s7, 31
	s_sub_i32 s6, s6, s7
	s_lshr_b32 s46, s6, 3
	s_and_b32 s6, s6, 7
	s_add_i32 s47, s22, s6

.LBB0_772:
	s_ashr_i32 s0, s0, 3
	s_add_i32 s0, s2, s0
	s_ashr_i32 s1, s0, 31
	s_lshr_b32 s1, s1, 26
	s_add_i32 s1, s0, s1
	s_ashr_i32 s2, s1, 6
	s_lshl_b32 s2, s2, 3
	s_sub_i32 s7, 64, s2
	s_min_i32 s7, s7, 8
	s_andn2_b32 s1, s1, 63
	s_sub_i32 s0, s0, s1
	s_lshr_b32 s48, s0, 3
	s_and_b32 s0, s0, 7
	s_add_i32 s50, s2, s0

.LBB0_1033:
	s_add_i32 s71, s71, 1
	s_mul_i32 s1, s71, s83
	s_mul_hi_u32 s2, s71, s3
	s_add_i32 s2, s2, s1
	s_mul_i32 s1, s71, s3
	s_add_u32 s4, s1, s94
	s_addc_u32 s5, s2, s84
	v_cmp_gt_i64_e32 vcc, s[4:5], v[196:197]
	v_cmp_lt_i64_e64 s[6:7], s[4:5], v[194:195]
	s_cbranch_vccnz .LBB0_1035
	s_ashr_i32 s1, s4, 31
	s_lshr_b32 s1, s1, 29
	s_add_i32 s1, s4, s1
	s_ashr_i32 s2, s1, 3
	s_and_b32 s1, s1, -8
	s_sub_i32 s1, s4, s1
	s_cmp_lt_i32 s1, 0
	s_cselect_b32 s4, 57, 56
	s_mul_i32 s1, s4, s1
	s_add_i32 s1, s1, s2
	s_mul_hi_i32 s2, s1, 0x92492493
	s_add_i32 s2, s2, s1
	s_lshr_b32 s4, s2, 31
	s_ashr_i32 s2, s2, 5
	s_add_i32 s2, s2, s4
	s_lshl_b32 s4, s2, 3
	s_sub_i32 s5, 64, s4
	s_min_i32 s5, s5, 8
	s_mul_i32 s2, s2, 56
	s_sub_i32 s1, s1, s2
	s_lshr_b32 s30, s1, 3
	s_and_b32 s1, s1, 7
	s_add_i32 s88, s1, s4

.LBB0_1629:
	s_ashr_i32 s22, s24, 3
	s_add_i32 s22, s26, s22
	s_ashr_i32 s23, s22, 31
	s_lshr_b32 s23, s23, 27
	s_add_i32 s23, s22, s23
	s_ashr_i32 s24, s23, 5
	s_lshl_b32 s24, s24, 3
	s_sub_i32 s25, 64, s24
	s_min_i32 s25, s25, 8
	s_andn2_b32 s23, s23, 31
	s_sub_i32 s23, s22, s23
	s_lshr_b32 s22, s23, 3
	s_and_b32 s23, s23, 7
	s_add_i32 s24, s24, s23

.LBB0_1761:
	s_add_i32 s44, s44, 1
	s_mul_i32 s6, s44, s15
	s_mul_hi_u32 s7, s44, s3
	s_add_i32 s7, s7, s6
	s_mul_i32 s6, s44, s3
	s_add_u32 s24, s6, s94
	s_addc_u32 s25, s7, s13
	v_cmp_gt_i64_e32 vcc, s[24:25], v[212:213]
	v_cmp_lt_i64_e64 s[6:7], s[24:25], v[210:211]
	s_cbranch_vccnz .LBB0_1763
	s_ashr_i32 s20, s24, 31
	s_lshr_b32 s20, s20, 29
	s_add_i32 s20, s24, s20
	s_ashr_i32 s21, s20, 3
	s_and_b32 s20, s20, -8
	s_sub_i32 s20, s24, s20
	s_cmp_lt_i32 s20, 0
	s_cselect_b32 s22, s33, 0xb0
	s_mul_i32 s20, s22, s20
	s_add_i32 s20, s20, s21
	s_mul_hi_i32 s21, s20, 0x2e8ba2e9
	s_lshr_b32 s22, s21, 31
	s_ashr_i32 s21, s21, 5
	s_add_i32 s21, s21, s22
	s_lshl_b32 s22, s21, 3
	s_sub_i32 s23, 64, s22
	s_min_i32 s23, s23, 8
	s_mulk_i32 s21, 0xb0
	s_sub_i32 s21, s20, s21
	s_lshr_b32 s20, s21, 3
	s_and_b32 s21, s21, 7
	s_add_i32 s22, s21, s22

.LBB0_2029:
	s_ashr_i32 s14, s14, 3
	s_add_i32 s14, s22, s14
	s_ashr_i32 s15, s14, 31
	s_lshr_b32 s15, s15, 27
	s_add_i32 s15, s14, s15
	s_ashr_i32 s20, s15, 5
	s_lshl_b32 s21, s20, 3
	s_sub_i32 s20, 64, s21
	s_min_i32 s22, s20, 8
	s_andn2_b32 s15, s15, 31
	s_sub_i32 s14, s14, s15
	s_lshr_b32 s20, s14, 3
	s_and_b32 s14, s14, 7
	s_add_i32 s22, s21, s14
